# scan raw q/k staging images: channel index swizzled by token-row half so the decay-prep column reads are bank-conflict free
# baseline (speedup 1.0000x reference)
; __device__ __forceinline__ int opaque_tid() { int t = threadIdx.x; asm volatile("" : "+v"(t)); return t; }
; #define LAS __attribute__((address_space(3)))
; __device__ __forceinline__ void scan_phase(LAS unsigned char* lds, bf16* proj, int G, int bid) {
;     const int tid = opaque_tid(), lane = tid & 63, wave = tid >> 6, fr = lane & 15, fq = lane >> 4;
;     constexpr int KRS = 132;
;     constexpr int SET = 34304, O_KR = 0, O_QR = 8448, O_QE = 16896, O_KE = 21248, O_KD = 25600, O_DV = 33792, O_VT = 2 * SET, QST = 272;
;     const int st = tid >> 4, sc8 = tid & 15;
;     const int pdk = tid >> 2, ptq = tid & 3;
;     const bool stager = tid < 256;
.LBB0_413:
	s_or_b64 exec, exec, s[0:1]
	v_readlane_b32 s0, v255, 33
	v_readlane_b32 s1, v255, 34
	s_xor_b64 s[0:1], s[0:1], -1
	v_writelane_b32 v255, s0, 46
	s_waitcnt lgkmcnt(0)
	s_barrier
	v_writelane_b32 v255, s1, 47
	s_nop 0
	v_readlane_b32 s0, v255, 39
	v_readlane_b32 s1, v255, 40
	s_and_b64 vcc, exec, s[0:1]
	s_mov_b64 s[0:1], -1
	s_cbranch_vccnz .LBB0_592
	v_readlane_b32 s4, v254, 43
	v_readlane_b32 s5, v254, 44
	s_and_b64 vcc, exec, s[4:5]
	s_cbranch_vccz .LBB0_496
	v_readlane_b32 s0, v253, 62
	v_readlane_b32 s1, v253, 63
	s_mov_b64 s[24:25], s[42:43]
	v_mov_b32_e32 v0, v209
	s_andn2_b64 vcc, exec, s[0:1]
	s_cbranch_vccnz .LBB0_444
	s_movk_i32 s0, 0x100
	v_ashrrev_i32_e32 v71, 2, v0
	v_cmp_gt_i32_e64 s[38:39], s0, v0
	s_movk_i32 s0, 0x200
	v_ashrrev_i32_e32 v70, 4, v0
	v_lshlrev_b32_e32 v72, 1, v71
	v_cmp_gt_i32_e64 s[42:43], s0, v0
	s_movk_i32 s0, 0x84
	v_and_b32_e32 v53, 15, v0
	v_add_u32_e32 v1, 0, v72
	s_waitcnt vmcnt(2)
	v_mul_lo_u32 v6, v70, s0
	v_add_u32_e32 v4, v1, v72
	v_bfe_u32 v5, v0, 4, 2
	v_lshlrev_b32_e32 v75, 2, v6
	v_lshlrev_b32_e32 v6, 5, v53
	s_waitcnt vmcnt(0)
	v_ashrrev_i32_e32 v8, 3, v0
	v_add3_u32 v76, 0, v75, v6
	v_lshlrev_b32_e32 v6, 9, v53
	v_readlane_b32 s4, v254, 11
	v_lshlrev_b32_e32 v8, 1, v8
	v_lshlrev_b32_e32 v9, 1, v70
	v_mad_u64_u32 v[54:55], s[0:1], v71, 60, v[4:5]
	v_and_b32_e32 v3, 3, v0
	v_add_u32_e32 v7, s4, v6
	v_and_b32_e32 v8, -16, v8
	v_and_b32_e32 v9, 6, v9
	s_movk_i32 s0, 0xffc4
	v_add3_u32 v77, v7, v8, v9
	v_mul_u32_u24_e32 v80, 0x210, v3
	v_mul_u32_u24_e32 v7, 0x220, v3
	v_mul_lo_u32 v84, v71, s0
	v_readlane_b32 s0, v254, 12
	v_lshl_add_u32 v81, v80, 2, v4
	v_lshl_add_u32 v82, v7, 1, v1
	v_and_b32_e32 v206, 12, v71
	v_lshlrev_b32_e32 v206, 1, v206
	v_bfe_u32 v207, v71, 4, 1
	v_lshl_or_b32 v206, v207, 2, v206
	v_and_b32_e32 v207, 3, v71
	v_or_b32_e32 v206, v206, v207
	v_and_b32_e32 v207, 0xffffffe0, v71
	v_or_b32_e32 v206, v206, v207
	v_lshlrev_b32_e32 v206, 1, v206
	v_sub_u32_e32 v82, v82, v72
	v_add_u32_e32 v82, v82, v206
	v_add_u32_e32 v1, s0, v6
	v_and_b32_e32 v4, -16, v71
	v_add3_u32 v85, v1, v8, v9
	v_and_b32_e32 v204, 3, v53
	v_lshlrev_b32_e32 v204, 4, v204
	v_xor_b32_e32 v77, v77, v204
	v_xor_b32_e32 v85, v85, v204
	v_bfe_u32 v204, v53, 2, 1
	v_lshlrev_b32_e32 v204, 6, v204
	v_sub_u32_e32 v180, v77, v204
	v_sub_u32_e32 v181, v85, v204
	v_add_u32_e32 v77, v77, v204
	v_add_u32_e32 v85, v85, v204
	v_lshlrev_b32_e32 v89, 4, v5
	v_lshlrev_b32_e32 v56, 3, v5
	v_lshlrev_b32_e32 v1, 2, v5
	v_ashrrev_i32_e32 v5, 31, v4
	v_lshl_add_u64 v[4:5], v[4:5], 1, s[82:83]
	v_mov_b32_e32 v57, v2
	v_lshlrev_b32_e32 v83, 6, v71
	v_lshl_add_u64 v[58:59], v[4:5], 0, v[56:57]
	v_lshlrev_b32_e32 v4, 4, v53
	v_mov_b32_e32 v5, v2
	s_movk_i32 s0, 0x10ff
	v_cmp_lt_i32_e64 s[40:41], s22, v0
	v_lshlrev_b32_e32 v73, 4, v0
	v_lshl_add_u64 v[60:61], s[82:83], 0, v[4:5]
	v_lshlrev_b32_e32 v57, 6, v53
	v_cmp_gt_u32_e64 s[48:49], v1, v53
	v_cmp_lt_u32_e64 s[50:51], v1, v53
	v_or_b32_e32 v4, 2, v1
	v_or_b32_e32 v1, 3, v1
	v_bitop3_b32 v92, v0, s0, 15 bitop3:0x6c
	v_and_b32_e32 v0, 0xfffffc00, v83
	v_cmp_gt_u32_e64 s[54:55], v1, v53
	v_lshlrev_b32_e32 v1, 10, v3
	v_or3_b32 v0, v0, v57, v89
	v_sub_u32_e32 v74, 0xff, v70
	v_lshlrev_b32_e32 v52, 3, v53
	v_add_u32_e32 v78, 16, v70
	v_sub_u32_e32 v79, 0xef, v70
	v_cmp_eq_u32_e64 s[44:45], 0, v3
	v_cmp_lt_u32_e64 s[46:47], 1, v3
	v_lshlrev_b32_e32 v55, 4, v3
	v_bfe_u32 v208, v209, 4, 2
	v_sub_u32_e32 v208, 0, v208
	v_and_b32_e32 v208, 3, v208
	v_lshlrev_b32_e32 v208, 4, v208
	v_xor_b32_e32 v55, v55, v208
	v_bfe_u32 v210, v209, 2, 2
	v_sub_u32_e32 v210, 0, v210
	v_and_b32_e32 v210, 3, v210
	v_bfe_u32 v212, v209, 4, 2
	v_xor_b32_e32 v210, v210, v212
	v_sub_u32_e32 v210, v210, v212
	v_lshlrev_b32_e32 v210, 4, v210
	v_add_u32_e32 v210, v210, v57
	v_add_u32_e32 v86, 32, v70
	v_sub_u32_e32 v87, 0xdf, v70
	v_mul_u32_u24_e32 v88, 0x110, v53
	v_cmp_gt_u32_e64 s[52:53], v4, v53
	v_sub_u32_e32 v90, 0, v1
	v_sub_u32_e32 v91, 0, v70
	v_lshrrev_b32_e32 v204, 5, v0
	v_and_b32_e32 v204, 0x70, v204
	v_xor_b32_e32 v0, v0, v204
	v_add_u32_e32 v93, s4, v0
	v_bfe_u32 v248, v209, 1, 1
	v_lshlrev_b32_e32 v248, 3, v248
	v_xor_b32_e32 v248, v248, v71
	v_sub_u32_e32 v249, v248, v71
	v_lshl_add_u32 v81, v249, 2, v81
	v_lshrrev_b32_e32 v249, 7, v209
	v_and_b32_e32 v249, 1, v249
	v_xor_b32_e32 v249, v249, v53
	v_lshlrev_b32_e32 v249, 5, v249
	v_add_u32_e32 v76, v75, v249
	v_and_b32_e32 v243, 15, v209
	v_lshlrev_b32_e32 v244, 9, v243
	v_bfe_u32 v245, v209, 4, 2
	v_bfe_u32 v246, v243, 2, 1
	v_xor_b32_e32 v246, v246, v245
	v_and_b32_e32 v246, 1, v246
	v_lshl_add_u32 v244, v246, 6, v244
	v_lshrrev_b32_e32 v246, 6, v209
	v_xor_b32_e32 v246, v246, v243
	v_and_b32_e32 v246, 3, v246
	v_lshl_add_u32 v244, v246, 4, v244
	v_lshrrev_b32_e32 v246, 1, v245
	v_lshl_add_u32 v244, v246, 2, v244
	v_add_u32_e32 v236, s4, v244
	v_and_b32_e32 v246, 1, v245
	v_mov_b32_e32 v237, 0x5040100
	v_mov_b32_e32 v247, 0x7060302
	v_cmp_eq_u32_e32 vcc, 1, v246
	s_nop 1
	v_cndmask_b32_e32 v237, v237, v247, vcc
	s_mov_b32 s13, s2
	s_branch .LBB0_418

; #define LAS __attribute__((address_space(3)))
; __device__ __forceinline__ void scan_phase(LAS unsigned char* lds, bf16* proj, int G, int bid) {
;     ...
;             SC_PREP(c + 1);
;             {
;                 const LAS unsigned char* qeb = set + O_QE + fr * QST; const LAS unsigned char* keb = set + O_KE + fr * QST;
;                 bf16x8 kaf[4], qbf[4];
; #pragma unroll
;                 for (int i = 0; i < 4; ++i) { kaf[i] = *(const LAS bf16x8*)(keb + (32 * i + fq * 8) * 2); qbf[i] = *(const LAS bf16x8*)(qeb + (32 * i + fq * 8) * 2); }
;                 u32x2 qlo[4], qhi[4];
; #pragma unroll
;                 for (int i = 0; i < 4; ++i) { qlo[i] = *(const LAS u32x2*)(qeb + (32 * i + fq * 4) * 2); qhi[i] = *(const LAS u32x2*)(qeb + (32 * i + 16 + fq * 4) * 2); }
;                 const bf16x8 vf = *(const LAS bf16x8*)(lds + O_VT + (c % 3) * 8192 + (wave * 16 + fr) * 64 + fq * 16);
;                 f32x4 pt = (f32x4){0.f, 0.f, 0.f, 0.f};
;                 __builtin_amdgcn_s_setprio(1);
; #pragma unroll
;                 for (int i = 0; i < 4; ++i) pt = __builtin_amdgcn_mfma_f32_16x16x32_bf16(kaf[i], qbf[i], pt, 0, 0, 0);
.LBB0_433:
	s_add_i32 s7, s6, 1
	s_bitcmp1_b32 s7, 0
	s_cselect_b32 s0, 0x8600, 0
	s_add_i32 s0, s0, 0
	v_lshl_add_u32 v1, v80, 2, s0
	v_lshl_add_u32 v0, v248, 2, v1
	ds_read2_b32 v[48:49], v0 offset1:132
	v_add_u32_e32 v3, 0x2000, v0
	ds_read2_b32 v[50:51], v3 offset0:64 offset1:196
	v_add_u32_e32 v3, 0x400, v0
	ds_read2_b32 v[98:99], v3 offset0:8 offset1:140
	v_add_u32_e32 v0, 0x2400, v0
	ds_read2_b32 v[100:101], v0 offset0:72 offset1:204
	s_waitcnt lgkmcnt(3)
	v_sub_f32_e32 v0, 1.0, v48
	v_max_f32_e32 v3, 0x3bdb8bac, v0
	v_sub_f32_e32 v0, 1.0, v49
	v_max_f32_e32 v0, 0x3bdb8bac, v0
	v_mul_f32_e32 v65, v3, v0
	s_waitcnt lgkmcnt(1)
	v_sub_f32_e32 v0, 1.0, v98
	v_max_f32_e32 v0, 0x3bdb8bac, v0
	v_mul_f32_e32 v104, v65, v0
	v_sub_f32_e32 v0, 1.0, v99
	v_max_f32_e32 v0, 0x3bdb8bac, v0
	v_mul_f32_e32 v105, v104, v0
	v_add3_u32 v1, v1, v90, v206
	s_nop 0
	v_mul_f32_dpp v0, v105, v105 quad_perm:[0,0,1,2] row_mask:0xf bank_mask:0xf bound_ctrl:1
	v_cndmask_b32_e64 v0, v0, v105, s[44:45]
	s_nop 1
	v_mul_f32_dpp v102, v0, v0 quad_perm:[0,0,0,1] row_mask:0xf bank_mask:0xf bound_ctrl:1
	v_cndmask_b32_e64 v102, v0, v102, s[46:47]
	v_mov_b32_e32 v0, 0
	s_nop 1
	v_mov_b32_dpp v0, v102 quad_perm:[0,0,1,2] row_mask:0xf bank_mask:0xf
	v_cndmask_b32_e64 v106, v0, 1.0, s[44:45]
	v_mov_b32_e32 v0, 0
	v_mul_f32_e32 v3, v3, v106
	s_nop 0
	v_mov_b32_dpp v0, v102 quad_perm:[3,3,3,3] row_mask:0xf bank_mask:0xf
	v_rcp_f32_e32 v102, v3
	v_mul_f32_e32 v3, v50, v3
	v_cvt_pk_bf16_f32 v3, v3, s0
	ds_write_b16 v1, v3 offset:16896
	v_mul_f32_e32 v3, v65, v106
	v_rcp_f32_e32 v103, v3
	v_mul_f32_e32 v3, v51, v3
	v_cvt_pk_bf16_f32 v3, v3, s0
	ds_write_b16 v1, v3 offset:17168
	v_mul_f32_e32 v3, v104, v106
	v_rcp_f32_e32 v50, v3
	s_waitcnt lgkmcnt(2)
	v_mul_f32_e32 v3, v100, v3
	v_cvt_pk_bf16_f32 v3, v3, s0
	ds_write_b16 v1, v3 offset:17440
	v_mul_f32_e32 v3, v105, v106
	v_rcp_f32_e32 v51, v3
	v_mul_f32_e32 v3, v101, v3
	v_cvt_pk_bf16_f32 v3, v3, s0
	v_pk_mul_f32 v[48:49], v[48:49], v[102:103]
	ds_write_b16 v1, v3 offset:17712
	v_cvt_pk_bf16_f32 v3, v48, s0
	ds_write_b16 v1, v3 offset:21248
	v_cvt_pk_bf16_f32 v3, v49, s0
	v_pk_mul_f32 v[50:51], v[98:99], v[50:51]
	ds_write_b16 v1, v3 offset:21520
	v_cvt_pk_bf16_f32 v3, v50, s0
	ds_write_b16 v1, v3 offset:21792
	v_cvt_pk_bf16_f32 v3, v51, s0
	v_pk_mul_f32 v[100:101], v[48:49], v[0:1] op_sel_hi:[1,0]
	v_pk_mul_f32 v[98:99], v[50:51], v[0:1] op_sel_hi:[1,0]
	ds_write_b16 v1, v3 offset:22064
	v_add_u32_e32 v1, s0, v83
	v_cvt_pk_bf16_f32 v48, v100, v101
	v_cvt_pk_bf16_f32 v49, v98, v99
	v_add_u32_e32 v3, v1, v55
	ds_write_b64 v3, v[48:49] offset:25600
	s_and_saveexec_b64 s[0:1], s[44:45]
	v_add_u32_e32 v1, v1, v84
	ds_write_b32 v1, v0 offset:33792
	s_or_b64 exec, exec, s[0:1]
	s_mul_hi_u32 s0, s6, 0xaaaaaaab
	s_lshr_b32 s0, s0, 1
	s_bitcmp1_b32 s6, 0
	s_cselect_b32 s1, 0x8600, 0
	s_add_i32 s14, s1, 0
	v_add_u32_e32 v0, s14, v88
	v_add_u32_e32 v1, v0, v89
	ds_read_b128 v[48:51], v1 offset:21248
	ds_read_b128 v[98:101], v1 offset:21312
	ds_read_b128 v[126:129], v1 offset:16896
	ds_read_b128 v[130:133], v1 offset:16960
	ds_read_b128 v[110:113], v1 offset:21376
	ds_read_b128 v[114:117], v1 offset:21440
	ds_read_b128 v[134:137], v1 offset:17024
	ds_read_b128 v[138:141], v1 offset:17088
	s_mulk_i32 s0, 0xa000
	v_add_u32_e32 v0, s0, v95
	ds_read_b128 v[142:145], v0
	s_setprio 1
	s_waitcnt lgkmcnt(6)
	v_mfma_f32_16x16x32_bf16 v[48:51], v[48:51], v[126:129], 0
	v_add_u32_e32 v0, s14, v89
	v_add_u32_e32 v1, v0, v210
	v_cvt_pk_bf16_f32 v146, v44, v45
	s_waitcnt lgkmcnt(5)
	v_mfma_f32_16x16x32_bf16 v[48:51], v[98:101], v[130:133], v[48:51]
	ds_read_b64 v[184:185], v1 offset:25600
	ds_read_b128 v[104:107], v0 offset:33792
	v_cvt_pk_bf16_f32 v147, v46, v47
	v_cvt_pk_bf16_f32 v148, v16, v17
	s_waitcnt lgkmcnt(4)
; #define LAS __attribute__((address_space(3)))
; __device__ __forceinline__ void scan_phase(LAS unsigned char* lds, bf16* proj, int G, int bid) {
;     ...
;                 for (int i = 0; i < 4; ++i) pt = __builtin_amdgcn_mfma_f32_16x16x32_bf16(kaf[i], qbf[i], pt, 0, 0, 0);
;                 f32x4 oacc = (f32x4){0.f, 0.f, 0.f, 0.f};
; #pragma unroll
;                 for (int i = 0; i < 4; ++i) {
;                     u32x4 sw; sw.x = cvt_pk_bf16(S[2 * i][0], S[2 * i][1]); sw.y = cvt_pk_bf16(S[2 * i][2], S[2 * i][3]); sw.z = cvt_pk_bf16(S[2 * i + 1][0], S[2 * i + 1][1]); sw.w = cvt_pk_bf16(S[2 * i + 1][2], S[2 * i + 1][3]);
;                     u32x4 qw; qw.x = qlo[i][0]; qw.y = qlo[i][1]; qw.z = qhi[i][0]; qw.w = qhi[i][1];
;                     oacc = __builtin_amdgcn_mfma_f32_16x16x32_bf16(__builtin_bit_cast(bf16x8, sw), __builtin_bit_cast(bf16x8, qw), oacc, 0, 0, 0);
;                 }
;                 const LAS float* dv = (const LAS float*)(set + O_DV);
; #pragma unroll
;                 for (int kt = 0; kt < 8; ++kt) {
;                     const f32x4 d4 = *(const LAS f32x4*)(dv + kt * 16 + fq * 4);
;                     const bf16x8 ka = *(const LAS bf16x8*)(set + O_KD + (kt * 16 + fr) * 64 + fq * 16);
;                     S[kt] = __builtin_amdgcn_mfma_f32_16x16x32_bf16(ka, vf, S[kt] * d4, 0, 0, 0);
;                 }
; #pragma unroll
;                 for (int j = 0; j < 4; ++j) pt[j] = (fq * 4 + j <= fr) ? pt[j] : 0.f;
;                 u32x4 pw; pw.x = cvt_pk_bf16(pt[0], pt[1]); pw.y = cvt_pk_bf16(pt[2], pt[3]); pw.z = 0u; pw.w = 0u;
;                 oacc = __builtin_amdgcn_mfma_f32_16x16x32_bf16(vf, __builtin_bit_cast(bf16x8, pw), oacc, 0, 0, 0);
;                 __builtin_amdgcn_s_setprio(0);
	v_mfma_f32_16x16x32_bf16 v[48:51], v[110:113], v[134:137], v[48:51]
	ds_read_b128 v[108:111], v0 offset:33856
	ds_read_b64 v[188:189], v1 offset:26624
	s_waitcnt lgkmcnt(2)
	v_pk_mul_f32 v[46:47], v[46:47], v[106:107]
	v_pk_mul_f32 v[44:45], v[44:45], v[104:105]
	ds_read_b64 v[232:233], v1 offset:32768
	s_waitcnt lgkmcnt(2)
	v_pk_mul_f32 v[16:17], v[16:17], v[108:109]
	v_mfma_f32_16x16x32_bf16 v[44:47], v[184:187], v[142:145], v[44:47]
	ds_read_b64 v[192:193], v1 offset:27648
	ds_read_b128 v[106:109], v0 offset:33920
	v_cvt_pk_bf16_f32 v149, v18, v19
	v_cvt_pk_bf16_f32 v150, v20, v21
	v_cvt_pk_bf16_f32 v151, v22, v23
	v_pk_mul_f32 v[18:19], v[18:19], v[110:111]
	s_waitcnt lgkmcnt(0)
	v_pk_mul_f32 v[22:23], v[22:23], v[108:109]
	v_pk_mul_f32 v[20:21], v[20:21], v[106:107]
	v_mfma_f32_16x16x32_bf16 v[16:19], v[188:191], v[142:145], v[16:19]
	ds_read_b128 v[110:113], v0 offset:33984
	ds_read_b64 v[196:197], v1 offset:28672
	v_cvt_pk_bf16_f32 v152, v24, v25
	v_cvt_pk_bf16_f32 v153, v26, v27
	v_mfma_f32_16x16x32_bf16 v[20:23], v[192:195], v[142:145], v[20:23]
	ds_read_b64 v[200:201], v1 offset:29696
	ds_read_b128 v[106:109], v0 offset:34048
	s_waitcnt lgkmcnt(3)
	v_pk_mul_f32 v[26:27], v[26:27], v[112:113]
	v_pk_mul_f32 v[24:25], v[24:25], v[110:111]
	v_cvt_pk_bf16_f32 v154, v28, v29
	v_cvt_pk_bf16_f32 v155, v30, v31
	s_waitcnt lgkmcnt(2)
	v_mfma_f32_16x16x32_bf16 v[24:27], v[196:199], v[142:145], v[24:27]
	ds_read_b64 v[224:225], v1 offset:30720
	ds_read_b128 v[118:121], v0 offset:34112
	s_waitcnt lgkmcnt(2)
	v_pk_mul_f32 v[30:31], v[30:31], v[108:109]
	v_pk_mul_f32 v[28:29], v[28:29], v[106:107]
	v_cvt_pk_bf16_f32 v156, v32, v33
	v_cvt_pk_bf16_f32 v157, v34, v35
	v_mfma_f32_16x16x32_bf16 v[28:31], v[200:203], v[142:145], v[28:31]
	ds_read_b128 v[98:101], v0 offset:34176
	s_waitcnt lgkmcnt(1)
	v_pk_mul_f32 v[34:35], v[34:35], v[120:121]
	v_pk_mul_f32 v[32:33], v[32:33], v[118:119]
	v_cvt_pk_bf16_f32 v102, v36, v37
	v_cvt_pk_bf16_f32 v103, v38, v39
	v_mfma_f32_16x16x32_bf16 v[32:35], v[224:227], v[142:145], v[32:35]
	ds_read_b128 v[110:113], v0 offset:34240
	s_waitcnt lgkmcnt(1)
	v_pk_mul_f32 v[38:39], v[38:39], v[100:101]
	v_pk_mul_f32 v[36:37], v[36:37], v[98:99]
	v_mfma_f32_16x16x32_bf16 v[98:101], v[146:149], v[126:129], 0
	v_cvt_pk_bf16_f32 v104, v40, v41
	ds_read_b64 v[228:229], v1 offset:31744
	v_cvt_pk_bf16_f32 v105, v42, v43
	v_mfma_f32_16x16x32_bf16 v[98:101], v[150:153], v[130:133], v[98:101]
	s_waitcnt lgkmcnt(1)
	v_pk_mul_f32 v[42:43], v[42:43], v[112:113]
	v_pk_mul_f32 v[40:41], v[40:41], v[110:111]
	v_mfma_f32_16x16x32_bf16 v[48:51], v[114:117], v[138:141], v[48:51]
	v_mfma_f32_16x16x32_bf16 v[98:101], v[154:157], v[134:137], v[98:101]
	v_mfma_f32_16x16x32_bf16 v[98:101], v[102:105], v[138:141], v[98:101]
	s_nop 5
	v_cvt_pk_bf16_f32 v0, v48, s0
	v_cvt_pk_bf16_f32 v1, v49, s0
	v_cndmask_b32_e64 v0, v0, 0, s[48:49]
	v_cndmask_b32_e64 v1, 0, v1, s[50:51]
	v_perm_b32 v0, v1, v0, s11
	v_cvt_pk_bf16_f32 v1, v50, s0
	v_cvt_pk_bf16_f32 v3, v51, s0
	v_cndmask_b32_e64 v1, v1, 0, s[52:53]
	v_cndmask_b32_e64 v3, v3, 0, s[54:55]
	v_perm_b32 v1, v3, v1, s11
	v_mov_b32_e32 v3, v2
	s_waitcnt lgkmcnt(0)
	v_mfma_f32_16x16x32_bf16 v[36:39], v[228:231], v[142:145], v[36:39]
	v_mfma_f32_16x16x32_bf16 v[40:43], v[232:235], v[142:145], v[40:43]
	v_mfma_f32_16x16x32_bf16 v[48:51], v[142:145], v[0:3], v[98:101]
	s_setprio 0
	s_mov_b64 s[0:1], -1
	s_cmp_gt_u32 s6, 15
	v_add_u32_e32 v1, s4, v53
	s_cbranch_scc0 .LBB0_437
	v_add_u32_e32 v0, 0xffffff00, v1
	v_cndmask_b32_e64 v0, v96, v0, s[56:57]
	v_add_u32_e32 v0, s5, v0
	s_mov_b64 s[0:1], 0

; #define SC_LOAD(c_) do { const bf16* rp_ = proj + (size_t)scan_row16(b, dir, (c_), st) * HIN + h * 128 + sc8 * 8; \
;         rq = *(const u32x4*)rp_; rk = *(const u32x4*)(rp_ + kcol - h * 128); rv = *(const u32x4*)(rp_ + 3072); } while (0)
; __device__ __forceinline__ void scan_phase(LAS unsigned char* lds, bf16* proj, int G, int bid) {
;     ...
;                     u32x2 ow; ow.x = cvt_pk_bf16(oacc[0], oacc[1]); ow.y = cvt_pk_bf16(oacc[2], oacc[3]);
;                     *(u32x2*)(proj + (size_t)scan_row16(b, dir, c, fr) * HIN + kcol + wave * 16 + fq * 4) = ow;
;                 }
;             }
;             if (stager) { if (c + 2 < 272) SC_WRITE(c + 2); if (c + 3 < 272) SC_LOAD(c + 3); }
.LBB0_439:
	s_nop 0
	v_cvt_pk_bf16_f32 v48, v48, v49
	v_cvt_pk_bf16_f32 v49, v50, v51
	v_mad_i64_i32 v[0:1], s[0:1], v0, s3, v[66:67]
	global_store_dwordx2 v[0:1], v[48:49], off
	s_and_saveexec_b64 s[0:1], s[38:39]
	s_cbranch_execz .LBB0_432
	s_cmpk_gt_u32 s6, 0x10d
	s_cbranch_scc1 .LBB0_442
	v_mov_b32_e32 v0, v249
	v_add3_u32 v0, s14, v75, v0
	s_add_i32 s14, s6, 2
	s_and_b32 s15, s14, 0xffff
	s_mul_i32 s15, s15, 0xaaab
	s_lshr_b32 s15, s15, 17
	s_mul_i32 s15, s15, 3
	s_sub_i32 s14, s14, s15
	s_and_b32 s14, s14, 0xffff
	v_lshl_add_u32 v1, s14, 13, v77
	v_lshl_add_u32 v205, s14, 13, v180
	v_lshl_add_u32 v242, s14, 13, v236
	s_waitcnt vmcnt(4)
	v_lshlrev_b32_e32 v48, 16, v12
	v_and_b32_e32 v49, 0xffff0000, v12
	v_lshlrev_b32_e32 v98, 16, v4
	v_and_b32_e32 v99, 0xffff0000, v4
	v_lshlrev_b32_e32 v50, 16, v13
	v_and_b32_e32 v51, 0xffff0000, v13
	v_lshlrev_b32_e32 v100, 16, v5
	v_and_b32_e32 v101, 0xffff0000, v5
	v_mov_b32_e32 v238, v8
	v_mov_b32_e32 v239, v9
	v_mov_b32_e32 v240, v10
	v_mov_b32_e32 v241, v11
	s_nop 1
	v_permlane16_swap_b32_e32 v8, v238
	v_permlane16_swap_b32_e32 v9, v239
	v_permlane16_swap_b32_e32 v10, v240
	v_permlane16_swap_b32_e32 v11, v241
	v_perm_b32 v238, v238, v8, v237
	v_perm_b32 v239, v239, v9, v237
	v_perm_b32 v240, v240, v10, v237
	v_perm_b32 v241, v241, v11, v237
	ds_write_b32 v242, v238 offset:0
	ds_write_b32 v242, v239 offset:128
	ds_write_b32 v242, v240 offset:256
	ds_write_b32 v242, v241 offset:384
	ds_write_b128 v0, v[48:51]
	ds_write_b128 v0, v[98:101] offset:8448
	v_lshlrev_b32_e32 v48, 16, v14
	v_and_b32_e32 v49, 0xffff0000, v14
	v_lshlrev_b32_e32 v98, 16, v6
	v_and_b32_e32 v99, 0xffff0000, v6
	v_lshlrev_b32_e32 v50, 16, v15
	v_and_b32_e32 v51, 0xffff0000, v15
	v_lshlrev_b32_e32 v100, 16, v7
	v_and_b32_e32 v101, 0xffff0000, v7
	ds_write_b128 v0, v[48:51] offset:16
	ds_write_b128 v0, v[98:101] offset:8464

; #define SC_LOAD(c_) do { const bf16* rp_ = proj + (size_t)scan_row16(b, dir, (c_), st) * HIN + h * 128 + sc8 * 8; \
;         rq = *(const u32x4*)rp_; rk = *(const u32x4*)(rp_ + kcol - h * 128); rv = *(const u32x4*)(rp_ + 3072); } while (0)
; __device__ __forceinline__ void scan_phase(LAS unsigned char* lds, bf16* proj, int G, int bid) {
;     ...
;                     u32x2 ow; ow.x = cvt_pk_bf16(oacc[0], oacc[1]); ow.y = cvt_pk_bf16(oacc[2], oacc[3]);
;                     *(u32x2*)(proj + (size_t)scan_row16(b, dir, c, fr) * HIN + kcol + wave * 16 + fq * 4) = ow;
;                 }
;             }
;             if (stager) { if (c + 2 < 272) SC_WRITE(c + 2); if (c + 3 < 272) SC_LOAD(c + 3); }
.LscanB_439:
	s_nop 0
	v_cvt_pk_bf16_f32 v48, v48, v49
	v_cvt_pk_bf16_f32 v49, v50, v51
	v_mad_i64_i32 v[0:1], s[0:1], v0, s3, v[66:67]
	global_store_dwordx2 v[0:1], v[48:49], off
	s_and_saveexec_b64 s[0:1], s[38:39]
	s_cbranch_execz .LscanB_432
	s_cmpk_gt_u32 s6, 0x10d
	s_cbranch_scc1 .LscanB_442
	v_mov_b32_e32 v0, v249
	v_add3_u32 v0, s14, v75, v0
	s_add_i32 s14, s6, 2
	s_and_b32 s15, s14, 0xffff
	s_mul_i32 s15, s15, 0xaaab
	s_lshr_b32 s15, s15, 17
	s_mul_i32 s15, s15, 3
	s_sub_i32 s14, s14, s15
	s_and_b32 s14, s14, 0xffff
	v_lshl_add_u32 v1, s14, 13, v77
	v_lshl_add_u32 v205, s14, 13, v180
	v_lshl_add_u32 v242, s14, 13, v236
	s_cmpk_eq_u32 s6, 0x10d
	s_cbranch_scc1 .LscanB_wtail
	s_waitcnt vmcnt(4)
	s_branch .LscanB_wgo
